# baseline (speedup 1.0000x reference)
.LBB0_704:
	v_mov_b32_e32 v14, v190
	v_readlane_b32 s7, v240, 49
	v_and_b32_e32 v15, 15, v14
	v_lshrrev_b32_e32 v0, 1, v14
	v_readlane_b32 s8, v240, 37
	v_and_or_b32 v2, v0, 24, s7
	v_lshlrev_b32_e32 v128, 12, v15
	v_readlane_b32 s9, v240, 38
	v_cmp_gt_u32_e32 vcc, 8, v15
	v_mov_b32_e32 v3, 0
	v_lshl_add_u64 v[0:1], s[8:9], 0, v[128:129]
	v_mov_b32_e32 v128, v2
	v_lshl_add_u64 v[10:11], v[128:129], 2, v[0:1]
	s_ashr_i32 s7, s6, 31
	s_lshl_b64 s[8:9], s[6:7], 11
	v_lshlrev_b32_e32 v1, 10, v15
	s_add_u32 s8, s0, s8
	s_addc_u32 s9, s1, s9
	v_lshlrev_b32_e32 v6, 1, v1
	v_mov_b32_e32 v7, v129
	v_lshl_add_u64 v[6:7], s[8:9], 0, v[6:7]
	v_lshlrev_b32_e32 v128, 1, v128
	v_lshl_add_u64 v[12:13], v[6:7], 0, v[128:129]
	v_mov_b32_e32 v20, 0
	v_mov_b32_e32 v21, 0
	v_mov_b32_e32 v22, 0
	v_mov_b32_e32 v23, 0
	v_mov_b32_e32 v24, 0
	v_mov_b32_e32 v25, 0
	v_mov_b32_e32 v26, 0
	v_mov_b32_e32 v27, 0
	v_mov_b32_e32 v28, 0
	v_mov_b32_e32 v29, 0
	v_mov_b32_e32 v30, 0
	v_mov_b32_e32 v31, 0
	v_mov_b32_e32 v32, 0
	v_mov_b32_e32 v33, 0
	v_mov_b32_e32 v34, 0
	v_mov_b32_e32 v35, 0
	v_mov_b32_e32 v36, 0
	v_mov_b32_e32 v37, 0
	v_mov_b32_e32 v38, 0
	v_mov_b32_e32 v39, 0
	v_mov_b32_e32 v40, 0
	v_mov_b32_e32 v41, 0
	v_mov_b32_e32 v42, 0
	v_mov_b32_e32 v43, 0
	v_mov_b32_e32 v44, 0
	v_mov_b32_e32 v45, 0
	v_mov_b32_e32 v46, 0
	v_mov_b32_e32 v47, 0
	v_mov_b32_e32 v48, 0
	v_mov_b32_e32 v49, 0
	v_mov_b32_e32 v50, 0
	v_mov_b32_e32 v51, 0
	s_and_saveexec_b64 s[8:9], vcc
	global_load_dwordx4 v[20:23], v[10:11], off
	global_load_dwordx4 v[24:27], v[10:11], off offset:16
	global_load_dwordx4 v[28:31], v[10:11], off offset:128
	global_load_dwordx4 v[32:35], v[10:11], off offset:144
	global_load_dwordx4 v[36:39], v[10:11], off offset:256
	global_load_dwordx4 v[40:43], v[10:11], off offset:272
	global_load_dwordx4 v[44:47], v[10:11], off offset:384
	global_load_dwordx4 v[48:51], v[10:11], off offset:400
	s_or_b64 exec, exec, s[8:9]
	global_load_dwordx4 v[52:55], v[12:13], off
	global_load_dwordx4 v[56:59], v[12:13], off offset:64
	global_load_dwordx4 v[60:63], v[12:13], off offset:128
	global_load_dwordx4 v[64:67], v[12:13], off offset:192
	s_waitcnt vmcnt(0)
	v_cvt_pk_bf16_f32 v20, v20, v21
	v_cvt_pk_bf16_f32 v21, v22, v23
	v_cvt_pk_bf16_f32 v22, v24, v25
	v_cvt_pk_bf16_f32 v23, v26, v27
	v_cvt_pk_bf16_f32 v28, v28, v29
	v_cvt_pk_bf16_f32 v29, v30, v31
	v_cvt_pk_bf16_f32 v30, v32, v33
	v_cvt_pk_bf16_f32 v31, v34, v35
	v_cvt_pk_bf16_f32 v36, v36, v37
	v_cvt_pk_bf16_f32 v37, v38, v39
	v_cvt_pk_bf16_f32 v38, v40, v41
	v_cvt_pk_bf16_f32 v39, v42, v43
	v_cvt_pk_bf16_f32 v44, v44, v45
	v_cvt_pk_bf16_f32 v45, v46, v47
	v_cvt_pk_bf16_f32 v46, v48, v49
	v_cvt_pk_bf16_f32 v47, v50, v51
	s_nop 1
	v_mfma_f32_16x16x32_bf16 v[0:3], v[20:23], v[52:55], 0
	v_mfma_f32_16x16x32_bf16 v[0:3], v[28:31], v[56:59], v[0:3]
	v_mfma_f32_16x16x32_bf16 v[0:3], v[36:39], v[60:63], v[0:3]
	v_mfma_f32_16x16x32_bf16 v[0:3], v[44:47], v[64:67], v[0:3]
	v_readlane_b32 s8, v240, 20
	v_readlane_b32 s9, v240, 21
	s_nop 2
	v_and_b32_e32 v4, 63, v14
	v_lshl_add_u32 v5, v4, 4, s33
	v_cmp_gt_u32_e32 vcc, 32, v4
	s_nop 1
	ds_write_b128 v5, v[0:3]
	s_and_b64 s[8:9], s[8:9], vcc
	v_mov_b32_e32 v2, 0
	v_mov_b32_e32 v3, 0
	v_mov_b32_e32 v0, 0
	v_mov_b32_e32 v1, 0
	s_waitcnt lgkmcnt(0)
	s_barrier
	s_and_saveexec_b64 s[10:11], s[8:9]
	s_cbranch_execz .LBB0_714
	v_lshl_add_u32 v10, v4, 4, 0
	ds_read_b128 v[0:3], v10
	s_waitcnt lgkmcnt(0)
	v_pk_add_f32 v[4:5], v[2:3], 0 op_sel_hi:[1,0]
	v_pk_add_f32 v[6:7], v[0:1], 0 op_sel_hi:[1,0]
	ds_read_b128 v[0:3], v10 offset:1024
	s_waitcnt lgkmcnt(0)
	v_pk_add_f32 v[4:5], v[2:3], v[4:5]
	v_pk_add_f32 v[6:7], v[0:1], v[6:7]
	ds_read_b128 v[0:3], v10 offset:2048
	s_waitcnt lgkmcnt(0)
	v_pk_add_f32 v[4:5], v[2:3], v[4:5]
	v_pk_add_f32 v[6:7], v[0:1], v[6:7]
	ds_read_b128 v[0:3], v10 offset:3072
	s_waitcnt lgkmcnt(0)
	v_pk_add_f32 v[4:5], v[2:3], v[4:5]
	v_pk_add_f32 v[6:7], v[0:1], v[6:7]
	ds_read_b128 v[0:3], v10 offset:4096
	s_waitcnt lgkmcnt(0)
	v_pk_add_f32 v[4:5], v[2:3], v[4:5]
	v_pk_add_f32 v[6:7], v[0:1], v[6:7]
	ds_read_b128 v[0:3], v10 offset:5120
	s_waitcnt lgkmcnt(0)
	v_pk_add_f32 v[4:5], v[2:3], v[4:5]
	v_pk_add_f32 v[6:7], v[0:1], v[6:7]
	ds_read_b128 v[0:3], v10 offset:6144
	s_waitcnt lgkmcnt(0)
	v_pk_add_f32 v[8:9], v[2:3], v[4:5]
	ds_read_b128 v[2:5], v10 offset:7168
	v_pk_add_f32 v[6:7], v[0:1], v[6:7]
	s_waitcnt lgkmcnt(0)
	v_pk_add_f32 v[0:1], v[4:5], v[8:9]
	v_pk_add_f32 v[2:3], v[2:3], v[6:7]

.LBB0_1015:
	v_mov_b32_e32 v16, v190
	s_ashr_i32 s5, s4, 31
	s_lshl_b64 s[6:7], s[4:5], 12
	v_lshrrev_b32_e32 v0, 1, v16
	v_and_b32_e32 v17, 15, v16
	v_and_b32_e32 v0, 24, v0
	v_readlane_b32 s8, v236, 1
	v_lshlrev_b32_e32 v128, 13, v17
	v_add_u32_e32 v0, s21, v0
	v_mov_b32_e32 v1, v129
	v_readlane_b32 s9, v236, 2
	s_add_u32 s6, s8, s6
	v_lshl_add_u64 v[10:11], v[0:1], 2, v[128:129]
	s_addc_u32 s7, s9, s7
	v_lshlrev_b32_e32 v128, 12, v17
	v_lshl_add_u64 v[2:3], s[6:7], 0, v[128:129]
	v_lshl_add_u64 v[12:13], v[0:1], 1, v[2:3]
	v_cmp_gt_u32_e64 s[40:41], 8, v17
	v_lshl_add_u64 v[8:9], s[80:81], 0, v[10:11]
	s_mov_b64 s[8:9], 0x110000
	v_lshl_add_u64 v[8:9], v[8:9], 0, s[8:9]
	v_lshl_add_u64 v[14:15], s[80:81], 0, v[12:13]
	v_add_co_u32_e32 v14, vcc, 0x2b600000, v14
	s_nop 1
	v_addc_co_u32_e32 v15, vcc, 0, v15, vcc
	v_mov_b32_e32 v22, 0
	v_mov_b32_e32 v23, 0
	v_mov_b32_e32 v24, 0
	v_mov_b32_e32 v25, 0
	v_mov_b32_e32 v26, 0
	v_mov_b32_e32 v27, 0
	v_mov_b32_e32 v28, 0
	v_mov_b32_e32 v29, 0
	v_mov_b32_e32 v30, 0
	v_mov_b32_e32 v31, 0
	v_mov_b32_e32 v32, 0
	v_mov_b32_e32 v33, 0
	v_mov_b32_e32 v34, 0
	v_mov_b32_e32 v35, 0
	v_mov_b32_e32 v36, 0
	v_mov_b32_e32 v37, 0
	v_mov_b32_e32 v38, 0
	v_mov_b32_e32 v39, 0
	v_mov_b32_e32 v40, 0
	v_mov_b32_e32 v41, 0
	v_mov_b32_e32 v42, 0
	v_mov_b32_e32 v43, 0
	v_mov_b32_e32 v44, 0
	v_mov_b32_e32 v45, 0
	v_mov_b32_e32 v46, 0
	v_mov_b32_e32 v47, 0
	v_mov_b32_e32 v48, 0
	v_mov_b32_e32 v49, 0
	v_mov_b32_e32 v50, 0
	v_mov_b32_e32 v51, 0
	v_mov_b32_e32 v52, 0
	v_mov_b32_e32 v53, 0
	s_and_saveexec_b64 s[6:7], s[40:41]
	global_load_dwordx4 v[22:25], v[8:9], off
	global_load_dwordx4 v[26:29], v[8:9], off offset:16
	global_load_dwordx4 v[30:33], v[8:9], off offset:128
	global_load_dwordx4 v[34:37], v[8:9], off offset:144
	global_load_dwordx4 v[38:41], v[8:9], off offset:256
	global_load_dwordx4 v[42:45], v[8:9], off offset:272
	global_load_dwordx4 v[46:49], v[8:9], off offset:384
	global_load_dwordx4 v[50:53], v[8:9], off offset:400
	s_or_b64 exec, exec, s[6:7]
	global_load_dwordx4 v[54:57], v[14:15], off
	global_load_dwordx4 v[58:61], v[14:15], off offset:64
	global_load_dwordx4 v[62:65], v[14:15], off offset:128
	global_load_dwordx4 v[66:69], v[14:15], off offset:192
	s_waitcnt vmcnt(0)
	v_cvt_pk_bf16_f32 v22, v22, v23
	v_cvt_pk_bf16_f32 v23, v24, v25
	v_cvt_pk_bf16_f32 v24, v26, v27
	v_cvt_pk_bf16_f32 v25, v28, v29
	v_cvt_pk_bf16_f32 v30, v30, v31
	v_cvt_pk_bf16_f32 v31, v32, v33
	v_cvt_pk_bf16_f32 v32, v34, v35
	v_cvt_pk_bf16_f32 v33, v36, v37
	v_cvt_pk_bf16_f32 v38, v38, v39
	v_cvt_pk_bf16_f32 v39, v40, v41
	v_cvt_pk_bf16_f32 v40, v42, v43
	v_cvt_pk_bf16_f32 v41, v44, v45
	v_cvt_pk_bf16_f32 v46, v46, v47
	v_cvt_pk_bf16_f32 v47, v48, v49
	v_cvt_pk_bf16_f32 v48, v50, v51
	v_cvt_pk_bf16_f32 v49, v52, v53
	s_nop 1
	v_mfma_f32_16x16x32_bf16 v[0:3], v[22:25], v[54:57], 0
	v_mfma_f32_16x16x32_bf16 v[0:3], v[30:33], v[58:61], v[0:3]
	v_mfma_f32_16x16x32_bf16 v[0:3], v[38:41], v[62:65], v[0:3]
	v_mfma_f32_16x16x32_bf16 v[0:3], v[46:49], v[66:69], v[0:3]
	s_and_saveexec_b64 s[6:7], s[40:41]
	global_load_dwordx4 v[22:25], v[8:9], off offset:512
	global_load_dwordx4 v[26:29], v[8:9], off offset:528
	global_load_dwordx4 v[30:33], v[8:9], off offset:640
	global_load_dwordx4 v[34:37], v[8:9], off offset:656
	global_load_dwordx4 v[38:41], v[8:9], off offset:768
	global_load_dwordx4 v[42:45], v[8:9], off offset:784
	global_load_dwordx4 v[46:49], v[8:9], off offset:896
	global_load_dwordx4 v[50:53], v[8:9], off offset:912
	s_or_b64 exec, exec, s[6:7]
	global_load_dwordx4 v[54:57], v[14:15], off offset:256
	global_load_dwordx4 v[58:61], v[14:15], off offset:320
	global_load_dwordx4 v[62:65], v[14:15], off offset:384
	global_load_dwordx4 v[66:69], v[14:15], off offset:448
	s_waitcnt vmcnt(0)
	v_cvt_pk_bf16_f32 v22, v22, v23
	v_cvt_pk_bf16_f32 v23, v24, v25
	v_cvt_pk_bf16_f32 v24, v26, v27
	v_cvt_pk_bf16_f32 v25, v28, v29
	v_cvt_pk_bf16_f32 v30, v30, v31
	v_cvt_pk_bf16_f32 v31, v32, v33
	v_cvt_pk_bf16_f32 v32, v34, v35
	v_cvt_pk_bf16_f32 v33, v36, v37
	v_cvt_pk_bf16_f32 v38, v38, v39
	v_cvt_pk_bf16_f32 v39, v40, v41
	v_cvt_pk_bf16_f32 v40, v42, v43
	v_cvt_pk_bf16_f32 v41, v44, v45
	v_cvt_pk_bf16_f32 v46, v46, v47
	v_cvt_pk_bf16_f32 v47, v48, v49
	v_cvt_pk_bf16_f32 v48, v50, v51
	v_cvt_pk_bf16_f32 v49, v52, v53
	s_nop 1
	v_mfma_f32_16x16x32_bf16 v[0:3], v[22:25], v[54:57], v[0:3]
	v_mfma_f32_16x16x32_bf16 v[0:3], v[30:33], v[58:61], v[0:3]
	v_mfma_f32_16x16x32_bf16 v[0:3], v[38:41], v[62:65], v[0:3]
	v_mfma_f32_16x16x32_bf16 v[0:3], v[46:49], v[66:69], v[0:3]
	s_nop 1
